# static s_setprio 1 for waves 4-7 during attention on the LDS-DMA structured loop
# baseline (speedup 1.0000x reference)
.Lp3_attn:
	v_readfirstlane_b32 s87, v208
	s_nop 3
	s_lshr_b32 s87, s87, 6
	s_cmp_ge_u32 s87, 4
	s_cbranch_scc0 .Lp3_prio_done
	s_setprio 1
